# v9 + attention unit prologue: four Q-fragment loads issued together with one wait (was load-wait-store x4)
# speedup vs baseline: 1.0103x; 1.0038x over previous
; #define LAS __attribute__((address_space(3)))
; __device__ __forceinline__ void fx_attn_unit(const Args& A, Frame& F, int bh, int qb, float qkmax) {
;     ...
;     const int b = bh >> 4, hd = bh & 15, q0 = qb * 256;
;     const bf16* Qg = (const bf16*)(A.ws + WS_BIG) + (size_t)b * SEQ * 4096 + hd * 64;
;     const bf16* Kg = Qg + 1024; const bf16* Vg = Qg + 2048; const bf16* Og = Qg + 3072;
;     const float* FLp = (const float*)(A.ws + WS_FL) + (size_t)bh * SEQ; const float* FTp = (const float*)(A.ws + WS_FT) + bh * 128;
;     const int tq = q0 + 32 * wave + l31;
;     LAS unsigned char* Qw = F.lds + 86016 + wave * 4096 + lane * 16;
; #pragma unroll
;     for (int ks = 0; ks < 4; ++ks) *(LAS u32x4*)(Qw + ks * 1024) = *(const u32x4*)(Qg + (size_t)tq * 4096 + 16 * ks + 8 * hh);
; __device__ __forceinline__ void fx_phase_attn(const Args& A, Frame& F0) {
;     ...
;     for (;;) {
;         if (F.tid == 0) slot[0] = __hip_atomic_fetch_add(qctr, 1u, __ATOMIC_RELAXED, __HIP_MEMORY_SCOPE_AGENT);
;         __syncthreads();
;         const unsigned i = slot[0];
;         __syncthreads();
;         if (i >= 2048u) break;
;         fx_attn_unit(A, F, (int)(i & 63u), 31 - (int)(i >> 6), qkmax);
.LBB0_678:
	s_or_b64 exec, exec, s[0:1]
	s_add_i32 s0, 0, 0x14000
	v_mov_b32_e32 v0, s0
	s_waitcnt lgkmcnt(0)
	s_barrier
	ds_read_b32 v0, v0
	s_movk_i32 s0, 0x7ff
	s_waitcnt lgkmcnt(0)
	s_barrier
	v_cmp_lt_u32_e32 vcc, s0, v0
	v_readfirstlane_b32 s46, v0
	s_mov_b64 s[0:1], -1
	s_cbranch_vccnz .LBB0_673
	s_lshr_b32 s47, s46, 6
	s_lshl_b32 s0, s46, 9
	s_sub_i32 s23, 31, s47
	s_and_b32 s22, s0, 0x6000
	s_and_b32 s35, s46, 63
	s_lshl_b32 s34, s23, 8
	s_lshl_b32 s0, s22, 13
	s_add_u32 s0, s92, s0
	s_addc_u32 s1, s93, 0
	s_lshl_b32 s20, s46, 6
	s_and_b32 s20, s20, 0x3c0
	s_lshl_b32 s24, s20, 1
	s_add_u32 s30, s0, s24
	s_addc_u32 s31, s1, 0
	s_add_i32 s33, s34, s4
	v_or_b32_e32 v120, s33, v115
	v_ashrrev_i32_e32 v121, 31, v120
	v_lshlrev_b64 v[2:3], 13, v[120:121]
	v_lshl_add_u64 v[118:119], s[30:31], 0, v[2:3]
	v_mov_b32_e32 v117, v1
	v_lshl_add_u64 v[6:7], v[118:119], 0, v[116:117]
	global_load_dwordx4 v[12:15], v[6:7], off
	global_load_dwordx4 v[16:19], v[6:7], off offset:32
	global_load_dwordx4 v[20:23], v[6:7], off offset:64
	global_load_dwordx4 v[24:27], v[6:7], off offset:96
	s_lshl_b32 s0, s35, 9
	v_readlane_b32 s1, v253, 29
	s_add_u32 s26, s1, s0
	v_readlane_b32 s0, v253, 30
	s_addc_u32 s27, s0, 0
	s_lshl_b32 s45, s23, 2
	s_add_i32 s25, s45, 4
	v_cmp_gt_u32_e64 s[0:1], s25, v110
	v_lshlrev_b32_e32 v0, 2, v110
	v_mov_b32_e32 v2, 0
	v_mov_b32_e32 v3, 0
	s_and_saveexec_b64 s[20:21], s[0:1]
	s_cbranch_execz .LBB0_681
	global_load_dword v3, v0, s[26:27]

; #define LAS __attribute__((address_space(3)))
; __device__ __forceinline__ void fx_attn_unit(const Args& A, Frame& F, int bh, int qb, float qkmax) {
;     ...
;     for (int ks = 0; ks < 4; ++ks) *(LAS u32x4*)(Qw + ks * 1024) = *(const u32x4*)(Qg + (size_t)tq * 4096 + 16 * ks + 8 * hh);
;     ...
;     { const float f0 = lane < NT ? FTp[lane] : 0.f, f1 = 64 + lane < NT ? FTp[64 + lane] : 0.f;
;       const float s0 = wave_scan_incl(f0, lane); const float s1 = __shfl(s0, 63) + wave_scan_incl(f1, lane);
.LBB0_683:
	s_or_b64 exec, exec, s[28:29]
	s_waitcnt vmcnt(0)
	ds_write_b128 v214, v[12:15]
	ds_write_b128 v214, v[16:19] offset:1024
	ds_write_b128 v214, v[20:23] offset:2048
	ds_write_b128 v214, v[24:27] offset:3072
	ds_bpermute_b32 v0, v180, v3
	ds_bpermute_b32 v4, v180, v2
	s_cmp_eq_u32 s47, 31
	v_mov_b32_e32 v5, 0
	s_waitcnt lgkmcnt(1)
	v_add_f32_e32 v0, v3, v0
	v_cndmask_b32_e64 v0, v0, v3, s[8:9]
	ds_bpermute_b32 v3, v181, v0
	s_waitcnt lgkmcnt(1)
	v_add_f32_e32 v4, v2, v4
	v_cndmask_b32_e64 v2, v4, v2, s[8:9]
	ds_bpermute_b32 v4, v181, v2
	s_waitcnt lgkmcnt(1)
	v_add_f32_e32 v3, v0, v3
	v_cndmask_b32_e64 v0, v3, v0, s[10:11]
	ds_bpermute_b32 v3, v200, v0
	s_waitcnt lgkmcnt(1)
	v_add_f32_e32 v4, v2, v4
	v_cndmask_b32_e64 v2, v4, v2, s[10:11]
	ds_bpermute_b32 v4, v200, v2
	s_waitcnt lgkmcnt(1)
	v_add_f32_e32 v3, v0, v3
	v_cndmask_b32_e64 v0, v3, v0, s[12:13]
	ds_bpermute_b32 v3, v201, v0
	s_waitcnt lgkmcnt(1)
	v_add_f32_e32 v4, v2, v4
	v_cndmask_b32_e64 v2, v4, v2, s[12:13]
	ds_bpermute_b32 v4, v201, v2
	s_waitcnt lgkmcnt(1)
	v_add_f32_e32 v3, v0, v3
	v_cndmask_b32_e64 v0, v3, v0, s[14:15]
	ds_bpermute_b32 v3, v202, v0
	s_waitcnt lgkmcnt(1)
	v_add_f32_e32 v4, v2, v4
	v_cndmask_b32_e64 v2, v4, v2, s[14:15]
	ds_bpermute_b32 v4, v202, v2
	s_waitcnt lgkmcnt(1)
	v_add_f32_e32 v3, v0, v3
	v_cndmask_b32_e64 v0, v3, v0, s[16:17]
	ds_bpermute_b32 v3, v203, v0
	s_waitcnt lgkmcnt(1)
	v_add_f32_e32 v4, v2, v4
	v_cndmask_b32_e64 v2, v4, v2, s[16:17]
	ds_bpermute_b32 v4, v203, v2
	s_waitcnt lgkmcnt(1)
	v_add_f32_e32 v3, v0, v3
	v_cndmask_b32_e64 v0, v3, v0, s[18:19]
	ds_bpermute_b32 v3, v204, v0
	s_waitcnt lgkmcnt(1)
	v_add_f32_e32 v4, v2, v4
	v_cndmask_b32_e64 v2, v4, v2, s[18:19]
	s_waitcnt lgkmcnt(0)
	v_add_f32_e32 v3, v2, v3
	v_mov_b32_e32 v2, 0
	s_cbranch_scc1 .LBB0_688
	s_add_i32 s47, s45, 63
	s_cmpk_lt_u32 s46, 0x3c0
	s_mov_b64 s[28:29], -1
	v_and_or_b32 v4, s47, 63, v194
	s_cbranch_scc0 .LBB0_686
	v_lshlrev_b32_e32 v5, 2, v4
	ds_bpermute_b32 v5, v5, v3
	s_mov_b64 s[28:29], 0
